# cache-policy hints: nt on rms row loads plus nt on the mlp1 (F, 512 MB) output stores
# speedup vs baseline: 1.0237x; 1.0157x over previous
.LBB0_75:
	v_lshl_add_u32 v144, s39, 8, v140
	v_lshl_add_u32 v138, s38, 8, v142
	v_ashrrev_i32_e32 v145, 31, v144
	v_ashrrev_i32_e32 v139, 31, v138
	v_lshlrev_b64 v[146:147], 13, v[144:145]
	v_max_f32_e32 v125, v125, v125
	v_max_f32_e32 v124, v124, v124
	v_max_f32_e32 v127, v127, v127
	v_max_f32_e32 v126, v126, v126
	v_max_f32_e32 v121, v121, v121
	v_max_f32_e32 v120, v120, v120
	v_max_f32_e32 v123, v123, v123
	v_max_f32_e32 v122, v122, v122
	v_lshl_add_u64 v[146:147], s[10:11], 0, v[146:147]
	v_lshlrev_b64 v[148:149], 1, v[138:139]
	v_max_f32_e32 v125, 0, v125
	v_max_f32_e32 v124, 0, v124
	v_max_f32_e32 v127, 0, v127
	v_max_f32_e32 v126, 0, v126
	v_max_f32_e32 v121, 0, v121
	v_max_f32_e32 v120, 0, v120
	v_max_f32_e32 v123, 0, v123
	v_max_f32_e32 v122, 0, v122
	v_lshl_add_u64 v[138:139], v[146:147], 0, v[148:149]
	v_pk_mul_f32 v[126:127], v[126:127], v[126:127]
	v_pk_mul_f32 v[124:125], v[124:125], v[124:125]
	v_pk_mul_f32 v[146:147], v[122:123], v[122:123]
	v_pk_mul_f32 v[122:123], v[120:121], v[120:121]
	v_max_f32_e32 v117, v117, v117
	v_max_f32_e32 v116, v116, v116
	v_max_f32_e32 v119, v119, v119
	v_max_f32_e32 v118, v118, v118
	v_max_f32_e32 v113, v113, v113
	v_max_f32_e32 v112, v112, v112
	v_max_f32_e32 v115, v115, v115
	v_max_f32_e32 v114, v114, v114
	v_cvt_pk_bf16_f32 v120, v124, v125
	v_cvt_pk_bf16_f32 v121, v126, v127
	v_cvt_pk_bf16_f32 v122, v122, v123
	v_cvt_pk_bf16_f32 v123, v146, v147
	v_max_f32_e32 v117, 0, v117
	v_max_f32_e32 v116, 0, v116
	v_max_f32_e32 v119, 0, v119
	v_max_f32_e32 v118, 0, v118
	v_max_f32_e32 v113, 0, v113
	v_max_f32_e32 v112, 0, v112
	v_max_f32_e32 v115, 0, v115
	v_max_f32_e32 v114, 0, v114
	global_store_dwordx4 v[138:139], v[120:123], off nt
	v_pk_mul_f32 v[118:119], v[118:119], v[118:119]
	v_pk_mul_f32 v[116:117], v[116:117], v[116:117]
	v_pk_mul_f32 v[120:121], v[114:115], v[114:115]
	v_pk_mul_f32 v[114:115], v[112:113], v[112:113]
	v_cvt_pk_bf16_f32 v112, v116, v117
	v_cvt_pk_bf16_f32 v113, v118, v119
	v_cvt_pk_bf16_f32 v114, v114, v115
	v_cvt_pk_bf16_f32 v115, v120, v121
	global_store_dwordx4 v[138:139], v[112:115], off offset:256 nt
	v_max_f32_e32 v109, v109, v109
	v_max_f32_e32 v108, v108, v108
	v_or_b32_e32 v112, 16, v144
	v_ashrrev_i32_e32 v113, 31, v112
	v_max_f32_e32 v111, v111, v111
	v_max_f32_e32 v110, v110, v110
	v_max_f32_e32 v105, v105, v105
	v_max_f32_e32 v104, v104, v104
	v_max_f32_e32 v107, v107, v107
	v_max_f32_e32 v106, v106, v106
	v_lshlrev_b64 v[112:113], 13, v[112:113]
	v_max_f32_e32 v109, 0, v109
	v_max_f32_e32 v108, 0, v108
	v_max_f32_e32 v111, 0, v111
	v_max_f32_e32 v110, 0, v110
	v_max_f32_e32 v105, 0, v105
	v_max_f32_e32 v104, 0, v104
	v_max_f32_e32 v107, 0, v107
	v_max_f32_e32 v106, 0, v106
	v_lshl_add_u64 v[112:113], s[10:11], 0, v[112:113]
	v_pk_mul_f32 v[110:111], v[110:111], v[110:111]
	v_pk_mul_f32 v[108:109], v[108:109], v[108:109]
	v_pk_mul_f32 v[114:115], v[106:107], v[106:107]
	v_pk_mul_f32 v[106:107], v[104:105], v[104:105]
	v_max_f32_e32 v101, v101, v101
	v_max_f32_e32 v100, v100, v100
	v_max_f32_e32 v103, v103, v103
	v_max_f32_e32 v102, v102, v102
	v_max_f32_e32 v97, v97, v97
	v_max_f32_e32 v96, v96, v96
	v_max_f32_e32 v99, v99, v99
	v_max_f32_e32 v98, v98, v98
	v_lshl_add_u64 v[112:113], v[112:113], 0, v[148:149]
	v_cvt_pk_bf16_f32 v104, v108, v109
	v_cvt_pk_bf16_f32 v105, v110, v111
	v_cvt_pk_bf16_f32 v106, v106, v107
	v_cvt_pk_bf16_f32 v107, v114, v115
	v_max_f32_e32 v101, 0, v101
	v_max_f32_e32 v100, 0, v100
	v_max_f32_e32 v103, 0, v103
	v_max_f32_e32 v102, 0, v102
	v_max_f32_e32 v97, 0, v97
	v_max_f32_e32 v96, 0, v96
	v_max_f32_e32 v99, 0, v99
	v_max_f32_e32 v98, 0, v98
	global_store_dwordx4 v[112:113], v[104:107], off nt
	v_pk_mul_f32 v[102:103], v[102:103], v[102:103]
	v_pk_mul_f32 v[100:101], v[100:101], v[100:101]
	v_pk_mul_f32 v[104:105], v[98:99], v[98:99]
	v_pk_mul_f32 v[98:99], v[96:97], v[96:97]
	v_cvt_pk_bf16_f32 v96, v100, v101
	v_cvt_pk_bf16_f32 v97, v102, v103
	v_cvt_pk_bf16_f32 v98, v98, v99
	v_cvt_pk_bf16_f32 v99, v104, v105
	global_store_dwordx4 v[112:113], v[96:99], off offset:256 nt
	v_max_f32_e32 v93, v93, v93
	v_max_f32_e32 v92, v92, v92
	v_or_b32_e32 v96, 32, v144
	v_ashrrev_i32_e32 v97, 31, v96
	v_max_f32_e32 v95, v95, v95
	v_max_f32_e32 v94, v94, v94
	v_max_f32_e32 v89, v89, v89
	v_max_f32_e32 v88, v88, v88
	v_max_f32_e32 v91, v91, v91
	v_max_f32_e32 v90, v90, v90
	v_lshlrev_b64 v[96:97], 13, v[96:97]
	v_max_f32_e32 v93, 0, v93
	v_max_f32_e32 v92, 0, v92
	v_max_f32_e32 v95, 0, v95
	v_max_f32_e32 v94, 0, v94
	v_max_f32_e32 v89, 0, v89
	v_max_f32_e32 v88, 0, v88
	v_max_f32_e32 v91, 0, v91
	v_max_f32_e32 v90, 0, v90
	v_lshl_add_u64 v[96:97], s[10:11], 0, v[96:97]
	v_pk_mul_f32 v[94:95], v[94:95], v[94:95]
	v_pk_mul_f32 v[92:93], v[92:93], v[92:93]
	v_pk_mul_f32 v[98:99], v[90:91], v[90:91]
	v_pk_mul_f32 v[90:91], v[88:89], v[88:89]
	v_max_f32_e32 v85, v85, v85
	v_max_f32_e32 v84, v84, v84
	v_max_f32_e32 v87, v87, v87
	v_max_f32_e32 v86, v86, v86
	v_max_f32_e32 v81, v81, v81
	v_max_f32_e32 v80, v80, v80
	v_max_f32_e32 v83, v83, v83
	v_max_f32_e32 v82, v82, v82
	v_lshl_add_u64 v[96:97], v[96:97], 0, v[148:149]
	v_cvt_pk_bf16_f32 v88, v92, v93
	v_cvt_pk_bf16_f32 v89, v94, v95
	v_cvt_pk_bf16_f32 v90, v90, v91
	v_cvt_pk_bf16_f32 v91, v98, v99
	v_max_f32_e32 v85, 0, v85
	v_max_f32_e32 v84, 0, v84
	v_max_f32_e32 v87, 0, v87
	v_max_f32_e32 v86, 0, v86
	v_max_f32_e32 v81, 0, v81
	v_max_f32_e32 v80, 0, v80
	v_max_f32_e32 v83, 0, v83
	v_max_f32_e32 v82, 0, v82
	global_store_dwordx4 v[96:97], v[88:91], off nt
	v_pk_mul_f32 v[86:87], v[86:87], v[86:87]
	v_pk_mul_f32 v[84:85], v[84:85], v[84:85]
	v_pk_mul_f32 v[88:89], v[82:83], v[82:83]
	v_pk_mul_f32 v[82:83], v[80:81], v[80:81]
	v_cvt_pk_bf16_f32 v80, v84, v85
	v_cvt_pk_bf16_f32 v81, v86, v87
	v_cvt_pk_bf16_f32 v82, v82, v83
	v_cvt_pk_bf16_f32 v83, v88, v89
	global_store_dwordx4 v[96:97], v[80:83], off offset:256 nt
	v_max_f32_e32 v77, v77, v77
	v_max_f32_e32 v76, v76, v76
	v_or_b32_e32 v80, 48, v144
	v_ashrrev_i32_e32 v81, 31, v80
	v_max_f32_e32 v79, v79, v79
	v_max_f32_e32 v78, v78, v78
	v_max_f32_e32 v73, v73, v73
	v_max_f32_e32 v72, v72, v72
	v_max_f32_e32 v75, v75, v75
	v_max_f32_e32 v74, v74, v74
	v_lshlrev_b64 v[80:81], 13, v[80:81]
	v_max_f32_e32 v77, 0, v77
	v_max_f32_e32 v76, 0, v76
	v_max_f32_e32 v79, 0, v79
	v_max_f32_e32 v78, 0, v78
	v_max_f32_e32 v73, 0, v73
	v_max_f32_e32 v72, 0, v72
	v_max_f32_e32 v75, 0, v75
	v_max_f32_e32 v74, 0, v74
	v_lshl_add_u64 v[80:81], s[10:11], 0, v[80:81]
	v_pk_mul_f32 v[78:79], v[78:79], v[78:79]
	v_pk_mul_f32 v[76:77], v[76:77], v[76:77]
	v_pk_mul_f32 v[82:83], v[74:75], v[74:75]
	v_pk_mul_f32 v[74:75], v[72:73], v[72:73]
	v_max_f32_e32 v69, v69, v69
	v_max_f32_e32 v68, v68, v68
	v_max_f32_e32 v71, v71, v71
	v_max_f32_e32 v70, v70, v70
	v_max_f32_e32 v65, v65, v65
	v_max_f32_e32 v64, v64, v64
	v_max_f32_e32 v67, v67, v67
	v_max_f32_e32 v66, v66, v66
	v_lshl_add_u64 v[80:81], v[80:81], 0, v[148:149]
	v_cvt_pk_bf16_f32 v72, v76, v77
	v_cvt_pk_bf16_f32 v73, v78, v79
	v_cvt_pk_bf16_f32 v74, v74, v75
	v_cvt_pk_bf16_f32 v75, v82, v83
	v_max_f32_e32 v69, 0, v69
	v_max_f32_e32 v68, 0, v68
	v_max_f32_e32 v71, 0, v71
	v_max_f32_e32 v70, 0, v70
	v_max_f32_e32 v65, 0, v65
	v_max_f32_e32 v64, 0, v64
	v_max_f32_e32 v67, 0, v67
	v_max_f32_e32 v66, 0, v66
	v_max_f32_e32 v61, v61, v61
	v_max_f32_e32 v60, v60, v60
	global_store_dwordx4 v[80:81], v[72:75], off nt
	v_pk_mul_f32 v[70:71], v[70:71], v[70:71]
	v_pk_mul_f32 v[68:69], v[68:69], v[68:69]
	v_pk_mul_f32 v[72:73], v[66:67], v[66:67]
	v_pk_mul_f32 v[66:67], v[64:65], v[64:65]
	v_max_f32_e32 v61, 0, v61
	v_max_f32_e32 v60, 0, v60
	v_max_f32_e32 v63, v63, v63
	v_max_f32_e32 v62, v62, v62
	v_max_f32_e32 v57, v57, v57
	v_max_f32_e32 v56, v56, v56
	v_max_f32_e32 v59, v59, v59
	v_max_f32_e32 v58, v58, v58
	v_cvt_pk_bf16_f32 v64, v68, v69
	v_cvt_pk_bf16_f32 v65, v70, v71
	v_cvt_pk_bf16_f32 v66, v66, v67
	v_cvt_pk_bf16_f32 v67, v72, v73
	v_max_f32_e32 v63, 0, v63
	v_max_f32_e32 v62, 0, v62
	v_max_f32_e32 v57, 0, v57
	v_max_f32_e32 v56, 0, v56
	v_max_f32_e32 v59, 0, v59
	v_max_f32_e32 v58, 0, v58
	v_pk_mul_f32 v[60:61], v[60:61], v[60:61]
	s_mov_b32 s13, 0x100000
	global_store_dwordx4 v[80:81], v[64:67], off offset:256 nt
	v_pk_mul_f32 v[62:63], v[62:63], v[62:63]
	v_max_f32_e32 v53, v53, v53
	v_pk_mul_f32 v[66:67], v[58:59], v[58:59]
	v_pk_mul_f32 v[58:59], v[56:57], v[56:57]
	v_cvt_pk_bf16_f32 v56, v60, v61
	v_add_co_u32_e32 v60, vcc, s13, v138
	v_max_f32_e32 v52, v52, v52
	v_max_f32_e32 v55, v55, v55
	v_max_f32_e32 v54, v54, v54
	v_max_f32_e32 v49, v49, v49
	v_max_f32_e32 v48, v48, v48
	v_max_f32_e32 v51, v51, v51
	v_max_f32_e32 v50, v50, v50
	v_cvt_pk_bf16_f32 v57, v62, v63
	v_cvt_pk_bf16_f32 v58, v58, v59
	v_cvt_pk_bf16_f32 v59, v66, v67
	v_addc_co_u32_e32 v61, vcc, 0, v139, vcc
	v_max_f32_e32 v53, 0, v53
	v_max_f32_e32 v52, 0, v52
	v_max_f32_e32 v55, 0, v55
	v_max_f32_e32 v54, 0, v54
	v_max_f32_e32 v49, 0, v49
	v_max_f32_e32 v48, 0, v48
	v_max_f32_e32 v51, 0, v51
	v_max_f32_e32 v50, 0, v50
	v_max_f32_e32 v45, v45, v45
	v_max_f32_e32 v44, v44, v44
	s_mov_b64 s[20:21], 0x100000
	global_store_dwordx4 v[60:61], v[56:59], off nt
	v_pk_mul_f32 v[54:55], v[54:55], v[54:55]
	v_pk_mul_f32 v[52:53], v[52:53], v[52:53]
	v_pk_mul_f32 v[56:57], v[50:51], v[50:51]
	v_pk_mul_f32 v[50:51], v[48:49], v[48:49]
	v_max_f32_e32 v45, 0, v45
	v_max_f32_e32 v44, 0, v44
	v_max_f32_e32 v47, v47, v47
	v_max_f32_e32 v46, v46, v46
	v_max_f32_e32 v41, v41, v41
	v_max_f32_e32 v40, v40, v40
	v_max_f32_e32 v43, v43, v43
	v_max_f32_e32 v42, v42, v42
	v_lshl_add_u64 v[64:65], v[138:139], 0, s[20:21]
	v_cvt_pk_bf16_f32 v48, v52, v53
	v_cvt_pk_bf16_f32 v49, v54, v55
	v_cvt_pk_bf16_f32 v50, v50, v51
	v_cvt_pk_bf16_f32 v51, v56, v57
	v_max_f32_e32 v47, 0, v47
	v_max_f32_e32 v46, 0, v46
	v_max_f32_e32 v41, 0, v41
	v_max_f32_e32 v40, 0, v40
	v_max_f32_e32 v43, 0, v43
	v_max_f32_e32 v42, 0, v42
	v_pk_mul_f32 v[44:45], v[44:45], v[44:45]
	s_mov_b32 s13, 0x120000
	global_store_dwordx4 v[64:65], v[48:51], off offset:256 nt
	v_pk_mul_f32 v[46:47], v[46:47], v[46:47]
	v_max_f32_e32 v37, v37, v37
	v_pk_mul_f32 v[50:51], v[42:43], v[42:43]
	v_pk_mul_f32 v[42:43], v[40:41], v[40:41]
	v_cvt_pk_bf16_f32 v40, v44, v45
	v_add_co_u32_e32 v44, vcc, s13, v138
	v_max_f32_e32 v36, v36, v36
	v_max_f32_e32 v39, v39, v39
	v_max_f32_e32 v38, v38, v38
	v_max_f32_e32 v33, v33, v33
	v_max_f32_e32 v32, v32, v32
	v_max_f32_e32 v35, v35, v35
	v_max_f32_e32 v34, v34, v34
	v_cvt_pk_bf16_f32 v41, v46, v47
	v_cvt_pk_bf16_f32 v42, v42, v43
	v_cvt_pk_bf16_f32 v43, v50, v51
	v_addc_co_u32_e32 v45, vcc, 0, v139, vcc
	v_max_f32_e32 v37, 0, v37
	v_max_f32_e32 v36, 0, v36
	v_max_f32_e32 v39, 0, v39
	v_max_f32_e32 v38, 0, v38
	v_max_f32_e32 v33, 0, v33
	v_max_f32_e32 v32, 0, v32
	v_max_f32_e32 v35, 0, v35
	v_max_f32_e32 v34, 0, v34
	v_max_f32_e32 v29, v29, v29
	v_max_f32_e32 v28, v28, v28
	s_mov_b64 s[20:21], 0x120000
	global_store_dwordx4 v[44:45], v[40:43], off nt
	v_pk_mul_f32 v[38:39], v[38:39], v[38:39]
	v_pk_mul_f32 v[36:37], v[36:37], v[36:37]
	v_pk_mul_f32 v[40:41], v[34:35], v[34:35]
	v_pk_mul_f32 v[34:35], v[32:33], v[32:33]
	v_max_f32_e32 v29, 0, v29
	v_max_f32_e32 v28, 0, v28
	v_max_f32_e32 v31, v31, v31
	v_max_f32_e32 v30, v30, v30
	v_max_f32_e32 v25, v25, v25
	v_max_f32_e32 v24, v24, v24
	v_max_f32_e32 v27, v27, v27
	v_max_f32_e32 v26, v26, v26
	v_lshl_add_u64 v[48:49], v[138:139], 0, s[20:21]
	v_cvt_pk_bf16_f32 v32, v36, v37
	v_cvt_pk_bf16_f32 v33, v38, v39
	v_cvt_pk_bf16_f32 v34, v34, v35
	v_cvt_pk_bf16_f32 v35, v40, v41
	v_max_f32_e32 v31, 0, v31
	v_max_f32_e32 v30, 0, v30
	v_max_f32_e32 v25, 0, v25
	v_max_f32_e32 v24, 0, v24
	v_max_f32_e32 v27, 0, v27
	v_max_f32_e32 v26, 0, v26
	v_pk_mul_f32 v[28:29], v[28:29], v[28:29]
	s_mov_b32 s13, 0x140000
	global_store_dwordx4 v[48:49], v[32:35], off offset:256 nt
	v_pk_mul_f32 v[30:31], v[30:31], v[30:31]
	v_max_f32_e32 v21, v21, v21
	v_pk_mul_f32 v[34:35], v[26:27], v[26:27]
	v_pk_mul_f32 v[26:27], v[24:25], v[24:25]
	v_cvt_pk_bf16_f32 v24, v28, v29
	v_add_co_u32_e32 v28, vcc, s13, v138
	v_max_f32_e32 v20, v20, v20
	v_max_f32_e32 v23, v23, v23
	v_max_f32_e32 v22, v22, v22
	v_max_f32_e32 v17, v17, v17
	v_max_f32_e32 v16, v16, v16
	v_max_f32_e32 v19, v19, v19
	v_max_f32_e32 v18, v18, v18
	v_cvt_pk_bf16_f32 v25, v30, v31
	v_cvt_pk_bf16_f32 v26, v26, v27
	v_cvt_pk_bf16_f32 v27, v34, v35
	v_addc_co_u32_e32 v29, vcc, 0, v139, vcc
	v_max_f32_e32 v21, 0, v21
	v_max_f32_e32 v20, 0, v20
	v_max_f32_e32 v23, 0, v23
	v_max_f32_e32 v22, 0, v22
	v_max_f32_e32 v17, 0, v17
	v_max_f32_e32 v16, 0, v16
	v_max_f32_e32 v19, 0, v19
	v_max_f32_e32 v18, 0, v18
	v_max_f32_e32 v13, v13, v13
	v_max_f32_e32 v12, v12, v12
	s_mov_b64 s[20:21], 0x140000
	global_store_dwordx4 v[28:29], v[24:27], off nt
	v_pk_mul_f32 v[22:23], v[22:23], v[22:23]
	v_pk_mul_f32 v[20:21], v[20:21], v[20:21]
	v_pk_mul_f32 v[24:25], v[18:19], v[18:19]
	v_pk_mul_f32 v[18:19], v[16:17], v[16:17]
	v_max_f32_e32 v13, 0, v13
	v_max_f32_e32 v12, 0, v12
	v_max_f32_e32 v15, v15, v15
	v_max_f32_e32 v14, v14, v14
	v_max_f32_e32 v9, v9, v9
	v_max_f32_e32 v8, v8, v8
	v_max_f32_e32 v11, v11, v11
	v_max_f32_e32 v10, v10, v10
	v_lshl_add_u64 v[32:33], v[138:139], 0, s[20:21]
	v_cvt_pk_bf16_f32 v16, v20, v21
	v_cvt_pk_bf16_f32 v17, v22, v23
	v_cvt_pk_bf16_f32 v18, v18, v19
	v_cvt_pk_bf16_f32 v19, v24, v25
	v_max_f32_e32 v15, 0, v15
	v_max_f32_e32 v14, 0, v14
	v_max_f32_e32 v9, 0, v9
	v_max_f32_e32 v8, 0, v8
	v_max_f32_e32 v11, 0, v11
	v_max_f32_e32 v10, 0, v10
	v_pk_mul_f32 v[12:13], v[12:13], v[12:13]
	s_mov_b32 s13, 0x160000
	global_store_dwordx4 v[32:33], v[16:19], off offset:256 nt
	v_pk_mul_f32 v[14:15], v[14:15], v[14:15]
	v_max_f32_e32 v5, v5, v5
	v_pk_mul_f32 v[18:19], v[10:11], v[10:11]
	v_pk_mul_f32 v[10:11], v[8:9], v[8:9]
	v_cvt_pk_bf16_f32 v8, v12, v13
	v_add_co_u32_e32 v12, vcc, s13, v138
	v_max_f32_e32 v4, v4, v4
	v_max_f32_e32 v7, v7, v7
	v_max_f32_e32 v6, v6, v6
	v_max_f32_e32 v1, v1, v1
	v_max_f32_e32 v0, v0, v0
	v_max_f32_e32 v3, v3, v3
	v_max_f32_e32 v2, v2, v2
	v_cvt_pk_bf16_f32 v9, v14, v15
	v_cvt_pk_bf16_f32 v10, v10, v11
	v_cvt_pk_bf16_f32 v11, v18, v19
	v_addc_co_u32_e32 v13, vcc, 0, v139, vcc
	v_max_f32_e32 v5, 0, v5
	v_max_f32_e32 v4, 0, v4
	v_max_f32_e32 v7, 0, v7
	v_max_f32_e32 v6, 0, v6
	v_max_f32_e32 v1, 0, v1
	v_max_f32_e32 v0, 0, v0
	v_max_f32_e32 v3, 0, v3
	v_max_f32_e32 v2, 0, v2
	s_mov_b64 s[20:21], 0x160000
	global_store_dwordx4 v[12:13], v[8:11], off nt
	v_pk_mul_f32 v[6:7], v[6:7], v[6:7]
	v_pk_mul_f32 v[4:5], v[4:5], v[4:5]
	v_pk_mul_f32 v[8:9], v[2:3], v[2:3]
	v_pk_mul_f32 v[2:3], v[0:1], v[0:1]
	v_lshl_add_u64 v[16:17], v[138:139], 0, s[20:21]
	v_cvt_pk_bf16_f32 v0, v4, v5
	v_cvt_pk_bf16_f32 v1, v6, v7
	v_cvt_pk_bf16_f32 v2, v2, v3
	v_cvt_pk_bf16_f32 v3, v8, v9
	s_andn2_b64 vcc, exec, s[6:7]
	s_mov_b64 s[6:7], -1
	global_store_dwordx4 v[16:17], v[0:3], off offset:256 nt
	s_cbranch_vccnz .LBB0_64
	s_and_b64 vcc, exec, s[4:5]
	s_cbranch_vccnz .LBB0_63
	s_barrier
	s_branch .LBB0_63
